# phase 7: the epilogue's gate / residual tile requests issued before the K-loop drain wait and its barriers
# speedup vs baseline: 1.0045x; 1.0045x over previous
; #define PG8_STAGE(bufoff, gbase, voff) do { _Pragma("unroll") for (int _i = 0; _i < 2; ++_i) \
;         __builtin_amdgcn_global_load_lds((const unsigned*)((const char*)(gbase) + (voff)[_i]), (LAS unsigned*)(lds + (bufoff) + ldsw + _i * 8192), 16, 0, 0); } while (0)
; #define PG8_LDA(dst, b, h) do { _Pragma("unroll") for (int m = 0; m < 4; ++m) _Pragma("unroll") for (int k = 0; k < 2; ++k) dst[m][k] = *(const LAS bf16x8*)(lds + PG8_SA(b, h) + aoff + m * 2048 + k * 1024); } while (0)
; #define PG8_WAIT_V(n) asm volatile("s_waitcnt vmcnt(" #n ")" ::: "memory")
; template <class Epi, class Sched, bool ZERO>
; __device__ __forceinline__ void gemm_phase_acc(LAS unsigned char* lds, const Gemm g, const Sched& S, const Epi& E, f32x4 (&acc)[2][2][4][2]) {
;     ...
;         for (int t = 0; t < nt; t += 2) {
;             const bool last = (t == nt - 2);
;             const char* a1 = cA + (size_t)(t + 1) * kstep;
;             const char* a2 = last ? nA : cA + (size_t)(t + 2) * kstep; const char* b2 = last ? nB : cB + (size_t)(t + 2) * kstep;
;             const char* a3 = a2 + kstep; const char* b3 = b2 + kstep;
;             PG8_LDB(B0, 0, 0); PG8_SCHED; PG8_LDA(At, 0, 0); PG8_STAGE(PG8_SA(1, 1), a1 + hstep, voffA);
;             PG8_WAIT_L(8); PG8_BAR; PG8_WAIT_L(0); PG8_MMA(0, 0, At, B0); PG8_BAR; PG8_SCHED;
;             PG8_LDB(B1, 0, 1); PG8_STAGE(PG8_SB(0, 0), b2, voffB);
;             PG8_BAR; PG8_WAIT_L(0); PG8_MMA(0, 1, At, B1); PG8_BAR;
;             PG8_LDA(At, 0, 1); PG8_STAGE(PG8_SA(0, 0), a2, voffA);
;             PG8_BAR; PG8_WAIT_L(0); PG8_MMA(1, 0, At, B0); PG8_BAR; PG8_SCHED;
;             PG8_STAGE(PG8_SB(0, 1), b2 + hstep, voffB);
;             PG8_WAIT_V(6); PG8_BAR; PG8_MMA(1, 1, At, B1); PG8_BAR;
;             PG8_LDB(B0, 1, 0); PG8_SCHED; PG8_LDA(At, 1, 0); PG8_STAGE(PG8_SA(0, 1), a2 + hstep, voffA);
;             PG8_WAIT_L(8); PG8_BAR; PG8_WAIT_L(0); PG8_MMA(0, 0, At, B0); PG8_BAR; PG8_SCHED;
;             PG8_LDB(B1, 1, 1); PG8_STAGE(PG8_SB(1, 0), b3, voffB);
;             PG8_BAR; PG8_WAIT_L(0); PG8_MMA(0, 1, At, B1); PG8_BAR;
;             PG8_LDA(At, 1, 1); PG8_STAGE(PG8_SA(1, 0), a3, voffA);
;             PG8_BAR; PG8_WAIT_L(0); PG8_MMA(1, 0, At, B0); PG8_BAR; PG8_SCHED;
;             PG8_STAGE(PG8_SB(1, 1), b3 + hstep, voffB);
;             PG8_WAIT_V(6); PG8_BAR; PG8_MMA(1, 1, At, B1); PG8_BAR;
.LBB0_1037:
	s_add_u32 s8, s20, s6
	ds_read_b128 v[146:149], v141
	ds_read_b128 v[150:153], v141 offset:1024
	ds_read_b128 v[154:157], v141 offset:2048
	ds_read_b128 v[158:161], v141 offset:3072
	s_addc_u32 s9, s21, s7
	s_add_u32 s8, s8, 0x7400100
	s_addc_u32 s9, s9, 0
	s_add_u32 s42, s19, s6
	s_addc_u32 s43, s28, s7
	s_cmpk_eq_i32 s6, 0x700
	s_cselect_b32 s11, s3, s9
	s_cselect_b32 s10, s2, s8
	s_cselect_b32 s9, s1, s43
	s_cselect_b32 s8, s0, s42
	s_mov_b32 m0, s30
	v_lshl_add_u64 v[194:195], v[136:137], 0, s[6:7]
	ds_read_b128 v[162:165], v142
	ds_read_b128 v[166:169], v142 offset:1024
	ds_read_b128 v[170:173], v142 offset:2048
	ds_read_b128 v[174:177], v142 offset:3072
	ds_read_b128 v[178:181], v142 offset:4096
	ds_read_b128 v[182:185], v142 offset:5120
	ds_read_b128 v[186:189], v142 offset:6144
	ds_read_b128 v[190:193], v142 offset:7168
	global_load_lds_dwordx4 v[194:195], off
	v_lshl_add_u64 v[194:195], v[138:139], 0, s[6:7]
	s_mov_b32 m0, s31
	s_nop 0
	global_load_lds_dwordx4 v[194:195], off
	s_waitcnt lgkmcnt(8)
	s_barrier
	s_waitcnt lgkmcnt(0)
	s_setprio 1
	s_waitcnt lgkmcnt(0)
	v_mfma_f32_16x16x32_bf16 v[124:127], v[146:149], v[162:165], v[124:127]
	v_mfma_f32_16x16x32_bf16 v[120:123], v[154:157], v[162:165], v[120:123]
	v_mfma_f32_16x16x32_bf16 v[108:111], v[146:149], v[170:173], v[108:111]
	v_mfma_f32_16x16x32_bf16 v[104:107], v[154:157], v[170:173], v[104:107]
	v_mfma_f32_16x16x32_bf16 v[92:95], v[146:149], v[178:181], v[92:95]
	v_mfma_f32_16x16x32_bf16 v[88:91], v[154:157], v[178:181], v[88:91]
	v_mfma_f32_16x16x32_bf16 v[76:79], v[146:149], v[186:189], v[76:79]
	v_mfma_f32_16x16x32_bf16 v[72:75], v[154:157], v[186:189], v[72:75]
	v_mfma_f32_16x16x32_bf16 v[124:127], v[150:153], v[166:169], v[124:127]
	v_mfma_f32_16x16x32_bf16 v[120:123], v[158:161], v[166:169], v[120:123]
	v_mfma_f32_16x16x32_bf16 v[108:111], v[150:153], v[174:177], v[108:111]
	v_mfma_f32_16x16x32_bf16 v[104:107], v[158:161], v[174:177], v[104:107]
	v_mfma_f32_16x16x32_bf16 v[92:95], v[150:153], v[182:185], v[92:95]
	v_mfma_f32_16x16x32_bf16 v[88:91], v[158:161], v[182:185], v[88:91]
	v_mfma_f32_16x16x32_bf16 v[76:79], v[150:153], v[190:193], v[76:79]
	v_mfma_f32_16x16x32_bf16 v[72:75], v[158:161], v[190:193], v[72:75]
	s_setprio 0
	s_barrier
	s_mov_b32 m0, s35
	v_lshl_add_u64 v[212:213], s[8:9], 0, v[132:133]
	ds_read_b128 v[194:197], v143
	ds_read_b128 v[198:201], v143 offset:1024
	ds_read_b128 v[202:205], v143 offset:2048
	ds_read_b128 v[206:209], v143 offset:3072
	global_load_lds_dwordx4 v[212:213], off
	v_lshl_add_u64 v[214:215], s[8:9], 0, v[128:129]
	s_mov_b32 m0, s38
	s_nop 0
	global_load_lds_dwordx4 v[214:215], off
	s_barrier
	s_waitcnt lgkmcnt(0)
	s_setprio 1
	s_waitcnt lgkmcnt(0)
	v_mfma_f32_16x16x32_bf16 v[116:119], v[194:197], v[162:165], v[116:119]
	v_mfma_f32_16x16x32_bf16 v[112:115], v[202:205], v[162:165], v[112:115]
	v_mfma_f32_16x16x32_bf16 v[100:103], v[194:197], v[170:173], v[100:103]
	v_mfma_f32_16x16x32_bf16 v[96:99], v[202:205], v[170:173], v[96:99]
	v_mfma_f32_16x16x32_bf16 v[84:87], v[194:197], v[178:181], v[84:87]
	v_mfma_f32_16x16x32_bf16 v[80:83], v[202:205], v[178:181], v[80:83]
	v_mfma_f32_16x16x32_bf16 v[68:71], v[194:197], v[186:189], v[68:71]
	v_mfma_f32_16x16x32_bf16 v[64:67], v[202:205], v[186:189], v[64:67]
	v_mfma_f32_16x16x32_bf16 v[116:119], v[198:201], v[166:169], v[116:119]
	v_mfma_f32_16x16x32_bf16 v[112:115], v[206:209], v[166:169], v[112:115]
	v_mfma_f32_16x16x32_bf16 v[100:103], v[198:201], v[174:177], v[100:103]
	v_mfma_f32_16x16x32_bf16 v[96:99], v[206:209], v[174:177], v[96:99]
	v_mfma_f32_16x16x32_bf16 v[84:87], v[198:201], v[182:185], v[84:87]
	v_mfma_f32_16x16x32_bf16 v[80:83], v[206:209], v[182:185], v[80:83]
	v_mfma_f32_16x16x32_bf16 v[68:71], v[198:201], v[190:193], v[68:71]
	v_mfma_f32_16x16x32_bf16 v[64:67], v[206:209], v[190:193], v[64:67]
	s_setprio 0
	s_mov_b32 m0, s15
	v_lshl_add_u64 v[216:217], s[10:11], 0, v[134:135]
	s_barrier
	ds_read_b128 v[162:165], v142 offset:16384
	ds_read_b128 v[166:169], v142 offset:17408
	ds_read_b128 v[170:173], v142 offset:18432
	ds_read_b128 v[174:177], v142 offset:19456
	ds_read_b128 v[178:181], v142 offset:20480
	ds_read_b128 v[182:185], v142 offset:21504
	ds_read_b128 v[186:189], v142 offset:22528
	ds_read_b128 v[190:193], v142 offset:23552
	global_load_lds_dwordx4 v[216:217], off
	v_lshl_add_u64 v[218:219], s[10:11], 0, v[130:131]
	s_mov_b32 m0, s16
	s_nop 0
	global_load_lds_dwordx4 v[218:219], off
	s_barrier
	s_waitcnt lgkmcnt(0)
	s_setprio 1
	s_waitcnt lgkmcnt(0)
	v_mfma_f32_16x16x32_bf16 v[60:63], v[146:149], v[162:165], v[60:63]
	v_mfma_f32_16x16x32_bf16 v[56:59], v[154:157], v[162:165], v[56:59]
	v_mfma_f32_16x16x32_bf16 v[44:47], v[146:149], v[170:173], v[44:47]
	v_mfma_f32_16x16x32_bf16 v[40:43], v[154:157], v[170:173], v[40:43]
	v_mfma_f32_16x16x32_bf16 v[28:31], v[146:149], v[178:181], v[28:31]
	v_mfma_f32_16x16x32_bf16 v[24:27], v[154:157], v[178:181], v[24:27]
	v_mfma_f32_16x16x32_bf16 v[12:15], v[146:149], v[186:189], v[12:15]
	v_mfma_f32_16x16x32_bf16 v[8:11], v[154:157], v[186:189], v[8:11]
	v_mfma_f32_16x16x32_bf16 v[60:63], v[150:153], v[166:169], v[60:63]
	v_mfma_f32_16x16x32_bf16 v[56:59], v[158:161], v[166:169], v[56:59]
	v_mfma_f32_16x16x32_bf16 v[44:47], v[150:153], v[174:177], v[44:47]
	v_mfma_f32_16x16x32_bf16 v[40:43], v[158:161], v[174:177], v[40:43]
	v_mfma_f32_16x16x32_bf16 v[28:31], v[150:153], v[182:185], v[28:31]
	v_mfma_f32_16x16x32_bf16 v[24:27], v[158:161], v[182:185], v[24:27]
	v_mfma_f32_16x16x32_bf16 v[12:15], v[150:153], v[190:193], v[12:15]
	v_mfma_f32_16x16x32_bf16 v[8:11], v[158:161], v[190:193], v[8:11]
	s_setprio 0
	s_barrier
; #define PG8_STAGE(bufoff, gbase, voff) do { _Pragma("unroll") for (int _i = 0; _i < 2; ++_i) \
;         __builtin_amdgcn_global_load_lds((const unsigned*)((const char*)(gbase) + (voff)[_i]), (LAS unsigned*)(lds + (bufoff) + ldsw + _i * 8192), 16, 0, 0); } while (0)
; #define PG8_LDA(dst, b, h) do { _Pragma("unroll") for (int m = 0; m < 4; ++m) _Pragma("unroll") for (int k = 0; k < 2; ++k) dst[m][k] = *(const LAS bf16x8*)(lds + PG8_SA(b, h) + aoff + m * 2048 + k * 1024); } while (0)
; #define PG8_WAIT_V(n) asm volatile("s_waitcnt vmcnt(" #n ")" ::: "memory")
; template <class Epi, class Sched, bool ZERO>
; __device__ __forceinline__ void gemm_phase_acc(LAS unsigned char* lds, const Gemm g, const Sched& S, const Epi& E, f32x4 (&acc)[2][2][4][2]) {
;     ...
;         for (int t = 0; t < nt; t += 2) {
;             const bool last = (t == nt - 2);
;             const char* a1 = cA + (size_t)(t + 1) * kstep;
;             const char* a2 = last ? nA : cA + (size_t)(t + 2) * kstep; const char* b2 = last ? nB : cB + (size_t)(t + 2) * kstep;
;             const char* a3 = a2 + kstep; const char* b3 = b2 + kstep;
;             PG8_LDB(B0, 0, 0); PG8_SCHED; PG8_LDA(At, 0, 0); PG8_STAGE(PG8_SA(1, 1), a1 + hstep, voffA);
;             PG8_WAIT_L(8); PG8_BAR; PG8_WAIT_L(0); PG8_MMA(0, 0, At, B0); PG8_BAR; PG8_SCHED;
;             PG8_LDB(B1, 0, 1); PG8_STAGE(PG8_SB(0, 0), b2, voffB);
;             PG8_BAR; PG8_WAIT_L(0); PG8_MMA(0, 1, At, B1); PG8_BAR;
;             PG8_LDA(At, 0, 1); PG8_STAGE(PG8_SA(0, 0), a2, voffA);
;             PG8_BAR; PG8_WAIT_L(0); PG8_MMA(1, 0, At, B0); PG8_BAR; PG8_SCHED;
;             PG8_STAGE(PG8_SB(0, 1), b2 + hstep, voffB);
;             PG8_WAIT_V(6); PG8_BAR; PG8_MMA(1, 1, At, B1); PG8_BAR;
;             PG8_LDB(B0, 1, 0); PG8_SCHED; PG8_LDA(At, 1, 0); PG8_STAGE(PG8_SA(0, 1), a2 + hstep, voffA);
;             PG8_WAIT_L(8); PG8_BAR; PG8_WAIT_L(0); PG8_MMA(0, 0, At, B0); PG8_BAR; PG8_SCHED;
;             PG8_LDB(B1, 1, 1); PG8_STAGE(PG8_SB(1, 0), b3, voffB);
;             PG8_BAR; PG8_WAIT_L(0); PG8_MMA(0, 1, At, B1); PG8_BAR;
;             PG8_LDA(At, 1, 1); PG8_STAGE(PG8_SA(1, 0), a3, voffA);
;             PG8_BAR; PG8_WAIT_L(0); PG8_MMA(1, 0, At, B0); PG8_BAR; PG8_SCHED;
;             PG8_STAGE(PG8_SB(1, 1), b3 + hstep, voffB);
;             PG8_WAIT_V(6); PG8_BAR; PG8_MMA(1, 1, At, B1); PG8_BAR;
	s_add_u32 s42, s8, 0x40000
	s_addc_u32 s43, s9, 0
	s_mov_b32 m0, s22
	v_lshl_add_u64 v[146:147], s[42:43], 0, v[132:133]
	global_load_lds_dwordx4 v[146:147], off
	v_lshl_add_u64 v[146:147], s[42:43], 0, v[128:129]
	s_mov_b32 m0, s39
	s_nop 0
	global_load_lds_dwordx4 v[146:147], off
	s_waitcnt vmcnt(6)
	s_barrier
	s_setprio 1
	v_mfma_f32_16x16x32_bf16 v[52:55], v[194:197], v[162:165], v[52:55]
	v_mfma_f32_16x16x32_bf16 v[48:51], v[202:205], v[162:165], v[48:51]
	v_mfma_f32_16x16x32_bf16 v[36:39], v[194:197], v[170:173], v[36:39]
	v_mfma_f32_16x16x32_bf16 v[32:35], v[202:205], v[170:173], v[32:35]
	v_mfma_f32_16x16x32_bf16 v[20:23], v[194:197], v[178:181], v[20:23]
	v_mfma_f32_16x16x32_bf16 v[16:19], v[202:205], v[178:181], v[16:19]
	v_mfma_f32_16x16x32_bf16 v[4:7], v[194:197], v[186:189], v[4:7]
	v_mfma_f32_16x16x32_bf16 v[0:3], v[202:205], v[186:189], v[0:3]
	v_mfma_f32_16x16x32_bf16 v[52:55], v[198:201], v[166:169], v[52:55]
	v_mfma_f32_16x16x32_bf16 v[48:51], v[206:209], v[166:169], v[48:51]
	v_mfma_f32_16x16x32_bf16 v[36:39], v[198:201], v[174:177], v[36:39]
	v_mfma_f32_16x16x32_bf16 v[32:35], v[206:209], v[174:177], v[32:35]
	v_mfma_f32_16x16x32_bf16 v[20:23], v[198:201], v[182:185], v[20:23]
	v_mfma_f32_16x16x32_bf16 v[16:19], v[206:209], v[182:185], v[16:19]
	v_mfma_f32_16x16x32_bf16 v[4:7], v[198:201], v[190:193], v[4:7]
	v_mfma_f32_16x16x32_bf16 v[0:3], v[206:209], v[190:193], v[0:3]
	s_setprio 0
	s_barrier
	ds_read_b128 v[146:149], v144
	ds_read_b128 v[150:153], v144 offset:1024
	ds_read_b128 v[154:157], v144 offset:2048
	ds_read_b128 v[158:161], v144 offset:3072
	s_add_u32 s10, s10, 0x40000
	s_addc_u32 s11, s11, 0
	s_mov_b32 m0, s24
	v_lshl_add_u64 v[194:195], s[10:11], 0, v[134:135]
	ds_read_b128 v[162:165], v142 offset:32768
	ds_read_b128 v[166:169], v142 offset:33792
	ds_read_b128 v[170:173], v142 offset:34816
	ds_read_b128 v[174:177], v142 offset:35840
	ds_read_b128 v[178:181], v142 offset:36864
	ds_read_b128 v[182:185], v142 offset:37888
	ds_read_b128 v[186:189], v142 offset:38912
	ds_read_b128 v[190:193], v142 offset:39936
	global_load_lds_dwordx4 v[194:195], off
	v_lshl_add_u64 v[194:195], s[10:11], 0, v[130:131]
	s_mov_b32 m0, s25
	s_nop 0
	global_load_lds_dwordx4 v[194:195], off
	s_waitcnt lgkmcnt(8)
	s_barrier
	s_waitcnt lgkmcnt(0)
	s_setprio 1
	s_waitcnt lgkmcnt(0)
	v_mfma_f32_16x16x32_bf16 v[124:127], v[146:149], v[162:165], v[124:127]
	v_mfma_f32_16x16x32_bf16 v[120:123], v[154:157], v[162:165], v[120:123]
	v_mfma_f32_16x16x32_bf16 v[108:111], v[146:149], v[170:173], v[108:111]
	v_mfma_f32_16x16x32_bf16 v[104:107], v[154:157], v[170:173], v[104:107]
	v_mfma_f32_16x16x32_bf16 v[92:95], v[146:149], v[178:181], v[92:95]
	v_mfma_f32_16x16x32_bf16 v[88:91], v[154:157], v[178:181], v[88:91]
	v_mfma_f32_16x16x32_bf16 v[76:79], v[146:149], v[186:189], v[76:79]
	v_mfma_f32_16x16x32_bf16 v[72:75], v[154:157], v[186:189], v[72:75]
	v_mfma_f32_16x16x32_bf16 v[124:127], v[150:153], v[166:169], v[124:127]
	v_mfma_f32_16x16x32_bf16 v[120:123], v[158:161], v[166:169], v[120:123]
	v_mfma_f32_16x16x32_bf16 v[108:111], v[150:153], v[174:177], v[108:111]
	v_mfma_f32_16x16x32_bf16 v[104:107], v[158:161], v[174:177], v[104:107]
	v_mfma_f32_16x16x32_bf16 v[92:95], v[150:153], v[182:185], v[92:95]
	v_mfma_f32_16x16x32_bf16 v[88:91], v[158:161], v[182:185], v[88:91]
	v_mfma_f32_16x16x32_bf16 v[76:79], v[150:153], v[190:193], v[76:79]
	v_mfma_f32_16x16x32_bf16 v[72:75], v[158:161], v[190:193], v[72:75]
	s_setprio 0
	s_barrier
	s_mov_b32 m0, s23
	v_lshl_add_u64 v[212:213], v[212:213], 0, s[4:5]
	ds_read_b128 v[194:197], v145
	ds_read_b128 v[198:201], v145 offset:1024
	ds_read_b128 v[202:205], v145 offset:2048
	ds_read_b128 v[206:209], v145 offset:3072
	global_load_lds_dwordx4 v[212:213], off
	v_lshl_add_u64 v[212:213], v[214:215], 0, s[4:5]
	s_mov_b32 m0, s40
	s_nop 0
	global_load_lds_dwordx4 v[212:213], off
	s_barrier
	s_waitcnt lgkmcnt(0)
	s_setprio 1
	s_waitcnt lgkmcnt(0)
	v_mfma_f32_16x16x32_bf16 v[116:119], v[194:197], v[162:165], v[116:119]
	v_mfma_f32_16x16x32_bf16 v[112:115], v[202:205], v[162:165], v[112:115]
	v_mfma_f32_16x16x32_bf16 v[100:103], v[194:197], v[170:173], v[100:103]
	v_mfma_f32_16x16x32_bf16 v[96:99], v[202:205], v[170:173], v[96:99]
	v_mfma_f32_16x16x32_bf16 v[84:87], v[194:197], v[178:181], v[84:87]
	v_mfma_f32_16x16x32_bf16 v[80:83], v[202:205], v[178:181], v[80:83]
	v_mfma_f32_16x16x32_bf16 v[68:71], v[194:197], v[186:189], v[68:71]
	v_mfma_f32_16x16x32_bf16 v[64:67], v[202:205], v[186:189], v[64:67]
	v_mfma_f32_16x16x32_bf16 v[116:119], v[198:201], v[166:169], v[116:119]
	v_mfma_f32_16x16x32_bf16 v[112:115], v[206:209], v[166:169], v[112:115]
	v_mfma_f32_16x16x32_bf16 v[100:103], v[198:201], v[174:177], v[100:103]
	v_mfma_f32_16x16x32_bf16 v[96:99], v[206:209], v[174:177], v[96:99]
	v_mfma_f32_16x16x32_bf16 v[84:87], v[198:201], v[182:185], v[84:87]
	v_mfma_f32_16x16x32_bf16 v[80:83], v[206:209], v[182:185], v[80:83]
	v_mfma_f32_16x16x32_bf16 v[68:71], v[198:201], v[190:193], v[68:71]
	v_mfma_f32_16x16x32_bf16 v[64:67], v[206:209], v[190:193], v[64:67]
	s_setprio 0
	s_mov_b32 m0, s26
	v_lshl_add_u64 v[212:213], v[216:217], 0, s[4:5]
	s_barrier
	ds_read_b128 v[162:165], v142 offset:49152
	ds_read_b128 v[166:169], v142 offset:50176
	ds_read_b128 v[170:173], v142 offset:51200
	ds_read_b128 v[174:177], v142 offset:52224
	ds_read_b128 v[178:181], v142 offset:53248
	ds_read_b128 v[182:185], v142 offset:54272
	ds_read_b128 v[186:189], v142 offset:55296
	ds_read_b128 v[190:193], v142 offset:56320
	global_load_lds_dwordx4 v[212:213], off
	v_lshl_add_u64 v[212:213], v[218:219], 0, s[4:5]
	s_mov_b32 m0, s27
	s_nop 0
	global_load_lds_dwordx4 v[212:213], off
	s_barrier
; #define PG8_LDA(dst, b, h) do { _Pragma("unroll") for (int m = 0; m < 4; ++m) _Pragma("unroll") for (int k = 0; k < 2; ++k) dst[m][k] = *(const LAS bf16x8*)(lds + PG8_SA(b, h) + aoff + m * 2048 + k * 1024); } while (0)
; template <class Epi, class Sched, bool ZERO>
; __device__ __forceinline__ void gemm_phase_acc(LAS unsigned char* lds, const Gemm g, const Sched& S, const Epi& E, f32x4 (&acc)[2][2][4][2]) {
;     ...
;             PG8_WAIT_V(6); PG8_BAR; PG8_MMA(1, 1, At, B1); PG8_BAR;
;             PG8_LDB(B0, 1, 0); PG8_SCHED; PG8_LDA(At, 1, 0); PG8_STAGE(PG8_SA(0, 1), a2 + hstep, voffA);
;             PG8_WAIT_L(8); PG8_BAR; PG8_WAIT_L(0); PG8_MMA(0, 0, At, B0); PG8_BAR; PG8_SCHED;
;             PG8_LDB(B1, 1, 1); PG8_STAGE(PG8_SB(1, 0), b3, voffB);
;             PG8_BAR; PG8_WAIT_L(0); PG8_MMA(0, 1, At, B1); PG8_BAR;
;             PG8_LDA(At, 1, 1); PG8_STAGE(PG8_SA(1, 0), a3, voffA);
;             PG8_BAR; PG8_WAIT_L(0); PG8_MMA(1, 0, At, B0); PG8_BAR; PG8_SCHED;
;             PG8_STAGE(PG8_SB(1, 1), b3 + hstep, voffB);
;             PG8_WAIT_V(6); PG8_BAR; PG8_MMA(1, 1, At, B1); PG8_BAR;
;         }
;         if constexpr (!Epi::AFTER_DRAIN) E(acc, cur, wr, wc, fr, fq);
;         if constexpr (Epi::DRAIN) __builtin_amdgcn_s_waitcnt(0x0F70);
;         if (!has_next) break;
; #pragma unroll
;         for (int a = 0; a < 2; ++a)
; #pragma unroll
;             for (int b = 0; b < 2; ++b)
; #pragma unroll
;                 for (int m = 0; m < 4; ++m)
; #pragma unroll
;                     for (int n = 0; n < 2; ++n) acc[a][b][m][n] = (f32x4){0.f, 0.f, 0.f, 0.f};
;         cur = nxt; cA = nA; cB = nB; ++ui;
;     }
;     PG8_WAIT_V(0);
;     if (wr == 0) PG8_BAR;
;     PG8_BAR;
;     __device__ __forceinline__ void fused(f32x4 (&acc)[2][2][4][2], const Unit& u, int wr, int wc, int fr, int fq, LAS unsigned char* lds) const {
;         const int b = u.pm >> 3;
;         const float* gv = (const float*)(ws + OFF_GATEV) + b * 1024 + u.pn * 256;
;         float* ssq = (float*)(ws + OFF_SSQ);
;         unsigned* cnt = (unsigned*)(ws + OFF_PCNT) + 64 * u.pm;
;         const int row0 = u.pm * 256 + wr * 64 + fr, col0 = wc * 32 + 8 * fq;
;         f32x4 gg[2][2];
; #pragma unroll
;         for (int bj = 0; bj < 2; ++bj)
; #pragma unroll
;             for (int n = 0; n < 2; ++n) gg[bj][n] = *(const f32x4*)(gv + col0 + bj * 128 + 4 * n);
;         f32x4 xb[2][2][2][2];
	s_waitcnt lgkmcnt(0)
	s_setprio 1
	s_waitcnt lgkmcnt(0)
	v_mfma_f32_16x16x32_bf16 v[60:63], v[146:149], v[162:165], v[60:63]
	v_mfma_f32_16x16x32_bf16 v[56:59], v[154:157], v[162:165], v[56:59]
	v_mfma_f32_16x16x32_bf16 v[44:47], v[146:149], v[170:173], v[44:47]
	v_mfma_f32_16x16x32_bf16 v[40:43], v[154:157], v[170:173], v[40:43]
	v_mfma_f32_16x16x32_bf16 v[28:31], v[146:149], v[178:181], v[28:31]
	v_mfma_f32_16x16x32_bf16 v[24:27], v[154:157], v[178:181], v[24:27]
	v_mfma_f32_16x16x32_bf16 v[12:15], v[146:149], v[186:189], v[12:15]
	v_mfma_f32_16x16x32_bf16 v[8:11], v[154:157], v[186:189], v[8:11]
	v_mfma_f32_16x16x32_bf16 v[60:63], v[150:153], v[166:169], v[60:63]
	v_mfma_f32_16x16x32_bf16 v[56:59], v[158:161], v[166:169], v[56:59]
	v_mfma_f32_16x16x32_bf16 v[44:47], v[150:153], v[174:177], v[44:47]
	v_mfma_f32_16x16x32_bf16 v[40:43], v[158:161], v[174:177], v[40:43]
	v_mfma_f32_16x16x32_bf16 v[28:31], v[150:153], v[182:185], v[28:31]
	v_mfma_f32_16x16x32_bf16 v[24:27], v[158:161], v[182:185], v[24:27]
	v_mfma_f32_16x16x32_bf16 v[12:15], v[150:153], v[190:193], v[12:15]
	v_mfma_f32_16x16x32_bf16 v[8:11], v[158:161], v[190:193], v[8:11]
	s_setprio 0
	s_barrier
	s_add_u32 s8, s8, 0x40080
	s_addc_u32 s9, s9, 0
	s_mov_b32 m0, s33
	v_lshl_add_u64 v[146:147], s[8:9], 0, v[132:133]
	global_load_lds_dwordx4 v[146:147], off
	v_lshl_add_u64 v[146:147], s[8:9], 0, v[128:129]
	s_mov_b32 m0, s41
	s_nop 0
	global_load_lds_dwordx4 v[146:147], off
	s_waitcnt vmcnt(6)
	s_barrier
	s_setprio 1
	v_mfma_f32_16x16x32_bf16 v[52:55], v[194:197], v[162:165], v[52:55]
	v_mfma_f32_16x16x32_bf16 v[48:51], v[202:205], v[162:165], v[48:51]
	v_mfma_f32_16x16x32_bf16 v[36:39], v[194:197], v[170:173], v[36:39]
	v_mfma_f32_16x16x32_bf16 v[32:35], v[202:205], v[170:173], v[32:35]
	v_mfma_f32_16x16x32_bf16 v[20:23], v[194:197], v[178:181], v[20:23]
	v_mfma_f32_16x16x32_bf16 v[16:19], v[202:205], v[178:181], v[16:19]
	v_mfma_f32_16x16x32_bf16 v[4:7], v[194:197], v[186:189], v[4:7]
	v_mfma_f32_16x16x32_bf16 v[0:3], v[202:205], v[186:189], v[0:3]
	v_mfma_f32_16x16x32_bf16 v[52:55], v[198:201], v[166:169], v[52:55]
	v_mfma_f32_16x16x32_bf16 v[48:51], v[206:209], v[166:169], v[48:51]
	v_mfma_f32_16x16x32_bf16 v[36:39], v[198:201], v[174:177], v[36:39]
	v_mfma_f32_16x16x32_bf16 v[32:35], v[206:209], v[174:177], v[32:35]
	v_mfma_f32_16x16x32_bf16 v[20:23], v[198:201], v[182:185], v[20:23]
	v_mfma_f32_16x16x32_bf16 v[16:19], v[206:209], v[182:185], v[16:19]
	v_mfma_f32_16x16x32_bf16 v[4:7], v[198:201], v[190:193], v[4:7]
	v_mfma_f32_16x16x32_bf16 v[0:3], v[206:209], v[190:193], v[0:3]
	s_setprio 0
	s_add_i32 s29, s29, 2
	s_add_u32 s6, s6, 0x100
	s_addc_u32 s7, s7, 0
	s_cmp_lt_u32 s29, 14
	s_barrier
	s_cbranch_scc1 .LBB0_1037
	s_lshl_b32 s0, s18, 7
	s_and_b32 s0, s0, 0xfffffc00
	s_ashr_i32 s1, s0, 31
	s_lshl_b64 s[0:1], s[0:1], 2
	s_add_u32 s0, s70, s0
	s_addc_u32 s1, s71, s1
	s_lshl_b32 s2, s54, 2
	v_lshlrev_b32_e32 v128, 3, v210
	s_add_u32 s0, s0, s2
	s_addc_u32 s1, s1, 0
	v_lshl_or_b32 v128, s13, 5, v128
	s_add_u32 s4, s70, 0xfc00000
	v_mov_b32_e32 v193, 0
	v_lshlrev_b32_e32 v192, 2, v128
	s_addc_u32 s5, s71, 0
	s_add_i32 s17, s17, s78
	v_lshl_add_u64 v[128:129], s[0:1], 0, v[192:193]
	s_mov_b32 s3, 0xfef9000
	v_add_co_u32_e32 v130, vcc, s3, v128
	v_or_b32_e32 v214, s17, v140
	s_add_u32 s6, s36, s2
	v_addc_co_u32_e32 v131, vcc, 0, v129, vcc
	s_addc_u32 s7, s37, 0
	v_ashrrev_i32_e32 v215, 31, v214
	global_load_dwordx4 v[136:139], v[130:131], off
	v_lshl_add_u64 v[212:213], s[6:7], 0, v[192:193]
	v_lshlrev_b64 v[130:131], 12, v[214:215]
	s_mov_b64 s[0:1], 0xfef9000
	v_lshl_add_u64 v[130:131], v[212:213], 0, v[130:131]
	global_load_dwordx4 v[200:203], v[130:131], off offset:16 nt
	global_load_dwordx4 v[196:199], v[130:131], off nt
	v_lshl_add_u64 v[128:129], v[128:129], 0, s[0:1]
	global_load_dwordx4 v[140:143], v[128:129], off offset:16
	global_load_dwordx4 v[132:135], v[128:129], off offset:512
	global_load_dwordx4 v[204:207], v[130:131], off offset:512 nt
	global_load_dwordx4 v[228:231], v[130:131], off offset:528 nt
	s_nop 0
	global_load_dwordx4 v[128:131], v[128:129], off offset:528
	v_or_b32_e32 v218, 16, v214
	v_ashrrev_i32_e32 v219, 31, v218
	v_lshlrev_b64 v[144:145], 12, v[218:219]
	v_or_b32_e32 v220, 32, v214
	v_lshl_add_u64 v[144:145], v[212:213], 0, v[144:145]
	v_ashrrev_i32_e32 v221, 31, v220
	global_load_dwordx4 v[184:187], v[144:145], off offset:16 nt
	global_load_dwordx4 v[188:191], v[144:145], off nt
	global_load_dwordx4 v[176:179], v[144:145], off offset:528 nt
	global_load_dwordx4 v[180:183], v[144:145], off offset:512 nt
	v_lshlrev_b64 v[144:145], 12, v[220:221]
	v_or_b32_e32 v216, 48, v214
	v_lshl_add_u64 v[144:145], v[212:213], 0, v[144:145]
	v_ashrrev_i32_e32 v217, 31, v216
	global_load_dwordx4 v[168:171], v[144:145], off offset:16 nt
	global_load_dwordx4 v[172:175], v[144:145], off nt
	global_load_dwordx4 v[160:163], v[144:145], off offset:528 nt
	global_load_dwordx4 v[164:167], v[144:145], off offset:512 nt
	v_lshlrev_b64 v[144:145], 12, v[216:217]
	v_lshl_add_u64 v[148:149], v[212:213], 0, v[144:145]
	global_load_dwordx4 v[152:155], v[148:149], off offset:16 nt
	global_load_dwordx4 v[156:159], v[148:149], off nt
	global_load_dwordx4 v[144:147], v[148:149], off offset:528 nt
	s_nop 0
	global_load_dwordx4 v[148:151], v[148:149], off offset:512 nt
	s_lshl_b32 s3, s34, 4
	s_add_u32 s3, s4, s3
	s_addc_u32 s7, s5, 0
	s_lshl_b32 s6, s13, 2
	s_add_u32 s6, s3, s6
	v_cmp_eq_u32_e64 s[0:1], 0, v210
	s_addc_u32 s7, s7, 0
	v_lshlrev_b64 v[210:211], 6, v[214:215]
	s_waitcnt vmcnt(0)
	s_cmpk_gt_u32 s14, 0xff
	s_cbranch_scc1 .LBB0_1040
	s_barrier
; #define EO_LOAD(k) do { _Pragma("unroll") for (int m2 = 0; m2 < 2; ++m2) _Pragma("unroll") for (int bj = 0; bj < 2; ++bj) _Pragma("unroll") for (int n = 0; n < 2; ++n) \
;             xb[(k) & 1][m2][bj][n] = __builtin_nontemporal_load((const f32x4*)(x + (size_t)(row0 + ((k) >> 1) * 128 + (((k) & 1) * 2 + m2) * 16) * 1024 + u.pn * 256 + col0 + bj * 128 + 4 * n)); } while (0)
;     __device__ __forceinline__ void fused(f32x4 (&acc)[2][2][4][2], const Unit& u, int wr, int wc, int fr, int fq, LAS unsigned char* lds) const {
;     ...
;         for (int k = 0; k < 4; ++k) { const int ai = k >> 1;
;             if (k + 1 < 4) EO_LOAD(k + 1);
; #pragma unroll
;             for (int m2 = 0; m2 < 2; ++m2) { const int m = (k & 1) * 2 + m2; const size_t row = (size_t)(row0 + ai * 128 + m * 16); float s = 0.f;
; #pragma unroll
;                 for (int bj = 0; bj < 2; ++bj)
; #pragma unroll
;                     for (int n = 0; n < 2; ++n) { const f32x4 o = xb[k & 1][m2][bj][n] + gg[bj][n] * acc[ai][bj][m][n];
;                         acc[ai][bj][m][n] = o; s += (o[0] * o[0] + o[1] * o[1]) + (o[2] * o[2] + o[3] * o[3]); }
;                 s += __shfl_xor(s, 16); s += __shfl_xor(s, 32);
;                 if (fq == 0) __hip_atomic_store(ssq + row * 16 + u.pn * 4 + wc, s, __ATOMIC_RELAXED, __HIP_MEMORY_SCOPE_AGENT); } }
.LBB0_1040:
	s_barrier
	s_waitcnt vmcnt(0)
	v_pk_fma_f32 v[200:201], v[120:121], v[140:141], v[200:201]
	v_pk_fma_f32 v[194:195], v[126:127], v[138:139], v[198:199]
	v_pk_fma_f32 v[196:197], v[124:125], v[136:137], v[196:197]
	v_pk_fma_f32 v[198:199], v[122:123], v[142:143], v[202:203]
	v_pk_fma_f32 v[202:203], v[118:119], v[134:135], v[206:207]
	v_pk_fma_f32 v[204:205], v[116:117], v[132:133], v[204:205]
	v_pk_fma_f32 v[206:207], v[114:115], v[130:131], v[230:231]
	v_pk_fma_f32 v[208:209], v[112:113], v[128:129], v[228:229]
	v_mul_f32_e32 v112, v197, v197
	v_mul_f32_e32 v113, v195, v195
	v_mul_f32_e32 v114, v201, v201
	v_mul_f32_e32 v115, v199, v199
	v_mul_f32_e32 v116, v205, v205
	v_mul_f32_e32 v117, v203, v203
	v_fmac_f32_e32 v112, v196, v196
	v_fmac_f32_e32 v113, v194, v194
	v_fmac_f32_e32 v114, v200, v200
	v_fmac_f32_e32 v115, v198, v198
	v_mul_f32_e32 v118, v209, v209
	v_mul_f32_e32 v119, v207, v207
	v_fmac_f32_e32 v116, v204, v204
	v_fmac_f32_e32 v117, v202, v202
	v_add_f32_e32 v112, v112, v113
	v_add_f32_e32 v113, v114, v115
	v_fmac_f32_e32 v118, v208, v208
	v_fmac_f32_e32 v119, v206, v206
	v_add_f32_e32 v114, v116, v117
	v_add_f32_e32 v112, v112, v113
	v_add_f32_e32 v112, v112, v114
	v_add_f32_e32 v113, v118, v119
	v_add_f32_e32 v112, v112, v113
	ds_bpermute_b32 v113, v225, v112
	s_waitcnt lgkmcnt(0)
	v_add_f32_e32 v112, v112, v113
	ds_bpermute_b32 v113, v226, v112
	s_and_saveexec_b64 s[8:9], s[0:1]
	s_cbranch_execz .LBB0_1042
	v_lshl_add_u64 v[114:115], s[6:7], 0, v[210:211]
	s_waitcnt lgkmcnt(0)
	v_add_f32_e32 v112, v112, v113
	global_store_dword v[114:115], v112, off sc1
